# speedup vs baseline: 1.0079x; 1.0031x over previous
; #define PG8_STAGE(bufoff, gbase, voff) do { _Pragma("unroll") for (int _i = 0; _i < 2; ++_i) \
;         __builtin_amdgcn_global_load_lds((const unsigned*)((const char*)(gbase) + (voff)[_i]), (LAS unsigned*)(lds + (bufoff) + ldsw + _i * 8192), 16, 0, 0); } while (0)
; #define PG8_LDA(dst, b, h) do { _Pragma("unroll") for (int m = 0; m < 4; ++m) _Pragma("unroll") for (int k = 0; k < 2; ++k) dst[m][k] = *(const LAS bf16x8*)(lds + PG8_SA(b, h) + aoff + m * 2048 + k * 1024); } while (0)
; __device__ __forceinline__ void gemm_phase(LAS unsigned char* lds, const GemmD& g) {
;     ...
;     f32x4 acc[2][2][4][2];
; #pragma unroll
;     for (int a = 0; a < 2; ++a)
; #pragma unroll
;         for (int b = 0; b < 2; ++b)
; #pragma unroll
;             for (int m = 0; m < 4; ++m)
; #pragma unroll
;                 for (int n = 0; n < 2; ++n) acc[a][b][m][n] = (f32x4){0.f, 0.f, 0.f, 0.f};
;     bf16x8 At[4][2], B0[2][2], B1[2][2];
;     const char* cA = (const char*)g.A + (size_t)cur.pm * tstep + (size_t)cur.k0 * kstep; const char* cB = (const char*)g.Bt + (size_t)cur.pn * tstep + (size_t)cur.k0 * kstep;
;     PG8_STAGE(PG8_SB(0, 0), cB, voffB); PG8_STAGE(PG8_SA(0, 0), cA, voffA); PG8_STAGE(PG8_SB(0, 1), cB + hstep, voffB); PG8_STAGE(PG8_SA(0, 1), cA + hstep, voffA);
;     if (wr == 1) PG8_BAR;
;     PG8_WAIT_V(4); PG8_BAR;
;     PG8_STAGE(PG8_SB(1, 0), cB + kstep, voffB); PG8_STAGE(PG8_SA(1, 0), cA + kstep, voffA); PG8_STAGE(PG8_SB(1, 1), cB + hstep + kstep, voffB);
;     PG8_WAIT_V(6); PG8_BAR;
;     for (;;) {
;         const bool has_next = unit_get(g, nM, nN, G, cblk, ui + 1, nxt);
;         const char* nA = has_next ? (const char*)g.A + (size_t)nxt.pm * tstep + (size_t)nxt.k0 * kstep : cA; const char* nB = has_next ? (const char*)g.Bt + (size_t)nxt.pn * tstep + (size_t)nxt.k0 * kstep : cB;
;         const int nt = cur.nt;
;         for (int t = 0; t < nt; t += 2) {
;             const bool last = (t == nt - 2);
;             const char* a1 = cA + (size_t)(t + 1) * kstep;
;             const char* a2 = last ? nA : cA + (size_t)(t + 2) * kstep; const char* b2 = last ? nB : cB + (size_t)(t + 2) * kstep;
;             const char* a3 = a2 + kstep; const char* b3 = b2 + kstep;
;             PG8_LDB(B0, 0, 0); PG8_SCHED; PG8_LDA(At, 0, 0); PG8_STAGE(PG8_SA(1, 1), a1 + hstep, voffA);
;             PG8_WAIT_L(8); PG8_BAR; PG8_WAIT_L(0); PG8_MMA(0, 0, At, B0); PG8_BAR; PG8_SCHED;
.LBB0_144:
	v_lshl_add_u64 v[132:133], v[2:3], 0, s[46:47]
	v_mov_b32_e32 v2, 0
	v_add_u32_e32 v135, -2, v134
	v_lshl_add_u64 v[130:131], v[4:5], 0, s[44:45]
	s_mov_b32 s4, 0
	v_mov_b32_e32 v3, v2
	v_mov_b32_e32 v4, v2
	v_mov_b32_e32 v5, v2
	v_mov_b32_e32 v6, v2
	v_mov_b32_e32 v7, v2
	v_mov_b32_e32 v8, v2
	v_mov_b32_e32 v9, v2
	v_mov_b32_e32 v18, v2
	v_mov_b32_e32 v19, v2
	v_mov_b32_e32 v20, v2
	v_mov_b32_e32 v21, v2
	v_mov_b32_e32 v22, v2
	v_mov_b32_e32 v23, v2
	v_mov_b32_e32 v24, v2
	v_mov_b32_e32 v25, v2
	v_mov_b32_e32 v34, v2
	v_mov_b32_e32 v35, v2
	v_mov_b32_e32 v36, v2
	v_mov_b32_e32 v37, v2
	v_mov_b32_e32 v38, v2
	v_mov_b32_e32 v39, v2
	v_mov_b32_e32 v40, v2
	v_mov_b32_e32 v41, v2
	v_mov_b32_e32 v50, v2
	v_mov_b32_e32 v51, v2
	v_mov_b32_e32 v52, v2
	v_mov_b32_e32 v53, v2
	v_mov_b32_e32 v54, v2
	v_mov_b32_e32 v55, v2
	v_mov_b32_e32 v56, v2
	v_mov_b32_e32 v57, v2
	v_mov_b32_e32 v10, v2
	v_mov_b32_e32 v11, v2
	v_mov_b32_e32 v12, v2
	v_mov_b32_e32 v13, v2
	v_mov_b32_e32 v14, v2
	v_mov_b32_e32 v15, v2
	v_mov_b32_e32 v16, v2
	v_mov_b32_e32 v17, v2
	v_mov_b32_e32 v26, v2
	v_mov_b32_e32 v27, v2
	v_mov_b32_e32 v28, v2
	v_mov_b32_e32 v29, v2
	v_mov_b32_e32 v30, v2
	v_mov_b32_e32 v31, v2
	v_mov_b32_e32 v32, v2
	v_mov_b32_e32 v33, v2
	v_mov_b32_e32 v42, v2
	v_mov_b32_e32 v43, v2
	v_mov_b32_e32 v44, v2
	v_mov_b32_e32 v45, v2
	v_mov_b32_e32 v46, v2
	v_mov_b32_e32 v47, v2
	v_mov_b32_e32 v48, v2
	v_mov_b32_e32 v49, v2
	v_mov_b32_e32 v58, v2
	v_mov_b32_e32 v59, v2
	v_mov_b32_e32 v60, v2
	v_mov_b32_e32 v61, v2
	v_mov_b32_e32 v62, v2
	v_mov_b32_e32 v63, v2
	v_mov_b32_e32 v64, v2
	v_mov_b32_e32 v65, v2
	v_mov_b32_e32 v66, v2
	v_mov_b32_e32 v67, v2
	v_mov_b32_e32 v68, v2
	v_mov_b32_e32 v69, v2
	v_mov_b32_e32 v70, v2
	v_mov_b32_e32 v71, v2
	v_mov_b32_e32 v72, v2
	v_mov_b32_e32 v73, v2
	s_waitcnt vmcnt(0)
	v_mov_b32_e32 v82, v2
	v_mov_b32_e32 v83, v2
	v_mov_b32_e32 v84, v2
	v_mov_b32_e32 v85, v2
	v_mov_b32_e32 v86, v2
	v_mov_b32_e32 v87, v2
	v_mov_b32_e32 v88, v2
	v_mov_b32_e32 v89, v2
	v_mov_b32_e32 v98, v2
	v_mov_b32_e32 v99, v2
	v_mov_b32_e32 v100, v2
	v_mov_b32_e32 v101, v2
	v_mov_b32_e32 v102, v2
	v_mov_b32_e32 v103, v2
	v_mov_b32_e32 v104, v2
	v_mov_b32_e32 v105, v2
	v_mov_b32_e32 v114, v2
	v_mov_b32_e32 v115, v2
	v_mov_b32_e32 v116, v2
	v_mov_b32_e32 v117, v2
	v_mov_b32_e32 v118, v2
	v_mov_b32_e32 v119, v2
	v_mov_b32_e32 v120, v2
	v_mov_b32_e32 v121, v2
	v_mov_b32_e32 v74, v2
	v_mov_b32_e32 v75, v2
	v_mov_b32_e32 v76, v2
	v_mov_b32_e32 v77, v2
	v_mov_b32_e32 v78, v2
	v_mov_b32_e32 v79, v2
	v_mov_b32_e32 v80, v2
	v_mov_b32_e32 v81, v2
	v_mov_b32_e32 v90, v2
	v_mov_b32_e32 v91, v2
	v_mov_b32_e32 v92, v2
	v_mov_b32_e32 v93, v2
	v_mov_b32_e32 v94, v2
	v_mov_b32_e32 v95, v2
	v_mov_b32_e32 v96, v2
	v_mov_b32_e32 v97, v2
	v_mov_b32_e32 v106, v2
	v_mov_b32_e32 v107, v2
	v_mov_b32_e32 v108, v2
	v_mov_b32_e32 v109, v2
	v_mov_b32_e32 v110, v2
	v_mov_b32_e32 v111, v2
	v_mov_b32_e32 v112, v2
	v_mov_b32_e32 v113, v2
	v_mov_b32_e32 v122, v2
	v_mov_b32_e32 v123, v2
	v_mov_b32_e32 v124, v2
	v_mov_b32_e32 v125, v2
	v_mov_b32_e32 v126, v2
	v_mov_b32_e32 v127, v2
	v_mov_b32_e32 v128, v2
	v_mov_b32_e32 v129, v2
	v_readfirstlane_b32 s5, v135
	s_lshr_b32 s5, s5, 1
	v_readfirstlane_b32 s98, v130
	v_readfirstlane_b32 s99, v131
	v_readfirstlane_b32 s100, v132
	v_readfirstlane_b32 s101, v133
	v_add_u32_e32 v242, s72, v172
	v_add_u32_e32 v243, s72, v168
	v_add_u32_e32 v244, 0x10000, v229
	v_add_u32_e32 v245, 0x14000, v229
	v_add_u32_e32 v246, 0x18000, v229
	v_add_u32_e32 v247, 0x1c000, v229
.LBB0_145:
	s_add_i32 s6, 0, 0x10000
	ds_read_b128 v[136:139], v244
	ds_read_b128 v[140:143], v244 offset:1024
	ds_read_b128 v[144:147], v244 offset:2048
	ds_read_b128 v[148:151], v244 offset:3072
	s_add_i32 m0, s2, 0xc000
	ds_read_b128 v[152:155], v233
	ds_read_b128 v[156:159], v233 offset:1024
	ds_read_b128 v[160:163], v233 offset:2048
	ds_read_b128 v[184:187], v233 offset:3072
	ds_read_b128 v[188:191], v233 offset:4096
	ds_read_b128 v[192:195], v233 offset:5120
	ds_read_b128 v[196:199], v233 offset:6144
	ds_read_b128 v[200:203], v233 offset:7168
	global_load_lds_dwordx4 v174, s[98:99]
	s_add_i32 m0, s2, 0xe000
	s_nop 0
	global_load_lds_dwordx4 v176, s[98:99]
	s_waitcnt lgkmcnt(8)
	s_barrier
	s_waitcnt lgkmcnt(0)
	v_mfma_f32_16x16x32_bf16 v[126:129], v[136:139], v[152:155], v[126:129]
	v_mfma_f32_16x16x32_bf16 v[122:125], v[144:147], v[152:155], v[122:125]
	v_mfma_f32_16x16x32_bf16 v[110:113], v[136:139], v[160:163], v[110:113]
	v_mfma_f32_16x16x32_bf16 v[106:109], v[144:147], v[160:163], v[106:109]
	v_mfma_f32_16x16x32_bf16 v[94:97], v[136:139], v[188:191], v[94:97]
	v_mfma_f32_16x16x32_bf16 v[90:93], v[144:147], v[188:191], v[90:93]
	v_mfma_f32_16x16x32_bf16 v[78:81], v[136:139], v[196:199], v[78:81]
	v_mfma_f32_16x16x32_bf16 v[74:77], v[144:147], v[196:199], v[74:77]
	v_mfma_f32_16x16x32_bf16 v[126:129], v[140:143], v[156:159], v[126:129]
	v_mfma_f32_16x16x32_bf16 v[122:125], v[148:151], v[156:159], v[122:125]
	v_mfma_f32_16x16x32_bf16 v[110:113], v[140:143], v[184:187], v[110:113]
	v_mfma_f32_16x16x32_bf16 v[106:109], v[148:151], v[184:187], v[106:109]
	v_mfma_f32_16x16x32_bf16 v[94:97], v[140:143], v[192:195], v[94:97]
	v_mfma_f32_16x16x32_bf16 v[90:93], v[148:151], v[192:195], v[90:93]
	v_mfma_f32_16x16x32_bf16 v[78:81], v[140:143], v[200:203], v[78:81]
	v_mfma_f32_16x16x32_bf16 v[74:77], v[148:151], v[200:203], v[74:77]
	s_barrier
	s_cmp_lg_u32 s5, 0
	s_cbranch_scc1 .Lkl_notlast
	v_readfirstlane_b32 s98, v180
	v_readfirstlane_b32 s99, v181
	v_readfirstlane_b32 s100, v182
	v_readfirstlane_b32 s101, v183
	s_branch .Lkl_ptr_done

; #define PG8_STAGE(bufoff, gbase, voff) do { _Pragma("unroll") for (int _i = 0; _i < 2; ++_i) \
;         __builtin_amdgcn_global_load_lds((const unsigned*)((const char*)(gbase) + (voff)[_i]), (LAS unsigned*)(lds + (bufoff) + ldsw + _i * 8192), 16, 0, 0); } while (0)
; #define PG8_LDA(dst, b, h) do { _Pragma("unroll") for (int m = 0; m < 4; ++m) _Pragma("unroll") for (int k = 0; k < 2; ++k) dst[m][k] = *(const LAS bf16x8*)(lds + PG8_SA(b, h) + aoff + m * 2048 + k * 1024); } while (0)
; #define PG8_LDB(dst, b, h) do { _Pragma("unroll") for (int n = 0; n < 2; ++n) _Pragma("unroll") for (int k = 0; k < 2; ++k) dst[n][k] = *(const LAS bf16x8*)(lds + PG8_SB(b, h) + boff + n * 2048 + k * 1024); } while (0)
; #define PG8_MMA(ai, bj, At, Bt) do { __builtin_amdgcn_s_setprio(1); _Pragma("unroll") for (int m = 0; m < 4; ++m) _Pragma("unroll") for (int n = 0; n < 2; ++n) _Pragma("unroll") for (int k = 0; k < 2; ++k) \
;         acc[ai][bj][m][n] = __builtin_amdgcn_mfma_f32_16x16x32_bf16(Bt[n][k], At[m][k], acc[ai][bj][m][n], 0, 0, 0); __builtin_amdgcn_s_setprio(0); } while (0)
; #define PG8_WAIT_V(n) asm volatile("s_waitcnt vmcnt(" #n ")" ::: "memory")
; #define PG8_WAIT_L(n) asm volatile("s_waitcnt lgkmcnt(" #n ")" ::: "memory")
; #define PG8_BAR __builtin_amdgcn_s_barrier()
; #define PG8_SCHED __builtin_amdgcn_sched_barrier(0)
; __device__ __forceinline__ void gemm_phase(LAS unsigned char* lds, const GemmD& g) {
;     ...
;             PG8_LDB(B1, 0, 1); PG8_STAGE(PG8_SB(0, 0), b2, voffB);
;             PG8_BAR; PG8_WAIT_L(0); PG8_MMA(0, 1, At, B1); PG8_BAR;
;             PG8_LDA(At, 0, 1); PG8_STAGE(PG8_SA(0, 0), a2, voffA);
;             PG8_BAR; PG8_WAIT_L(0); PG8_MMA(1, 0, At, B0); PG8_BAR; PG8_SCHED;
;             PG8_STAGE(PG8_SB(0, 1), b2 + hstep, voffB);
;             PG8_WAIT_V(6); PG8_BAR; PG8_MMA(1, 1, At, B1); PG8_BAR;
;             PG8_LDB(B0, 1, 0); PG8_SCHED; PG8_LDA(At, 1, 0); PG8_STAGE(PG8_SA(0, 1), a2 + hstep, voffA);
;             PG8_WAIT_L(8); PG8_BAR; PG8_WAIT_L(0); PG8_MMA(0, 0, At, B0); PG8_BAR; PG8_SCHED;
.Lkl_ptr_done:
	s_add_i32 s4, 0, 0x14000
	s_add_i32 s6, s6, s87
	s_mov_b32 m0, s6
	ds_read_b128 v[204:207], v245
	ds_read_b128 v[208:211], v245 offset:1024
	ds_read_b128 v[234:237], v245 offset:2048
	ds_read_b128 v[238:241], v245 offset:3072
	global_load_lds_dwordx4 v172, s[100:101]
	s_add_i32 m0, s6, 0x2000
	s_nop 0
	global_load_lds_dwordx4 v168, s[100:101]
	s_barrier
	s_waitcnt lgkmcnt(0)
	v_mfma_f32_16x16x32_bf16 v[118:121], v[204:207], v[152:155], v[118:121]
	v_mfma_f32_16x16x32_bf16 v[114:117], v[234:237], v[152:155], v[114:117]
	v_mfma_f32_16x16x32_bf16 v[102:105], v[204:207], v[160:163], v[102:105]
	v_mfma_f32_16x16x32_bf16 v[98:101], v[234:237], v[160:163], v[98:101]
	v_mfma_f32_16x16x32_bf16 v[86:89], v[204:207], v[188:191], v[86:89]
	v_mfma_f32_16x16x32_bf16 v[82:85], v[234:237], v[188:191], v[82:85]
	v_mfma_f32_16x16x32_bf16 v[70:73], v[204:207], v[196:199], v[70:73]
	v_mfma_f32_16x16x32_bf16 v[66:69], v[234:237], v[196:199], v[66:69]
	v_mfma_f32_16x16x32_bf16 v[118:121], v[208:211], v[156:159], v[118:121]
	v_mfma_f32_16x16x32_bf16 v[114:117], v[238:241], v[156:159], v[114:117]
	v_mfma_f32_16x16x32_bf16 v[102:105], v[208:211], v[184:187], v[102:105]
	v_mfma_f32_16x16x32_bf16 v[98:101], v[238:241], v[184:187], v[98:101]
	v_mfma_f32_16x16x32_bf16 v[86:89], v[208:211], v[192:195], v[86:89]
	v_mfma_f32_16x16x32_bf16 v[82:85], v[238:241], v[192:195], v[82:85]
	v_mfma_f32_16x16x32_bf16 v[70:73], v[208:211], v[200:203], v[70:73]
	v_mfma_f32_16x16x32_bf16 v[66:69], v[238:241], v[200:203], v[66:69]
	s_barrier
	s_mov_b32 m0, s2
	ds_read_b128 v[152:155], v233 offset:16384
	ds_read_b128 v[156:159], v233 offset:17408
	ds_read_b128 v[160:163], v233 offset:18432
	ds_read_b128 v[184:187], v233 offset:19456
	ds_read_b128 v[188:191], v233 offset:20480
	ds_read_b128 v[192:195], v233 offset:21504
	ds_read_b128 v[196:199], v233 offset:22528
	ds_read_b128 v[200:203], v233 offset:23552
	global_load_lds_dwordx4 v170, s[98:99]
	s_mov_b32 m0, s3
	s_nop 0
	global_load_lds_dwordx4 v166, s[98:99]
	s_barrier
	s_waitcnt lgkmcnt(0)
	v_mfma_f32_16x16x32_bf16 v[62:65], v[136:139], v[152:155], v[62:65]
	v_mfma_f32_16x16x32_bf16 v[58:61], v[144:147], v[152:155], v[58:61]
	v_mfma_f32_16x16x32_bf16 v[46:49], v[136:139], v[160:163], v[46:49]
	v_mfma_f32_16x16x32_bf16 v[42:45], v[144:147], v[160:163], v[42:45]
	v_mfma_f32_16x16x32_bf16 v[30:33], v[136:139], v[188:191], v[30:33]
	v_mfma_f32_16x16x32_bf16 v[26:29], v[144:147], v[188:191], v[26:29]
	v_mfma_f32_16x16x32_bf16 v[14:17], v[136:139], v[196:199], v[14:17]
	v_mfma_f32_16x16x32_bf16 v[10:13], v[144:147], v[196:199], v[10:13]
	v_mfma_f32_16x16x32_bf16 v[62:65], v[140:143], v[156:159], v[62:65]
	v_mfma_f32_16x16x32_bf16 v[58:61], v[148:151], v[156:159], v[58:61]
	v_mfma_f32_16x16x32_bf16 v[46:49], v[140:143], v[184:187], v[46:49]
	v_mfma_f32_16x16x32_bf16 v[42:45], v[148:151], v[184:187], v[42:45]
	v_mfma_f32_16x16x32_bf16 v[30:33], v[140:143], v[192:195], v[30:33]
	v_mfma_f32_16x16x32_bf16 v[26:29], v[148:151], v[192:195], v[26:29]
	v_mfma_f32_16x16x32_bf16 v[14:17], v[140:143], v[200:203], v[14:17]
	v_mfma_f32_16x16x32_bf16 v[10:13], v[148:151], v[200:203], v[10:13]
	s_barrier
	s_add_i32 s4, s4, s87
	s_mov_b32 m0, s4
	s_nop 0
	global_load_lds_dwordx4 v242, s[100:101]
	s_add_i32 m0, s4, 0x2000
	s_nop 0
	global_load_lds_dwordx4 v243, s[100:101]
	s_waitcnt vmcnt(6)
	s_barrier
	v_mfma_f32_16x16x32_bf16 v[54:57], v[204:207], v[152:155], v[54:57]
	v_mfma_f32_16x16x32_bf16 v[50:53], v[234:237], v[152:155], v[50:53]
	v_mfma_f32_16x16x32_bf16 v[38:41], v[204:207], v[160:163], v[38:41]
	v_mfma_f32_16x16x32_bf16 v[34:37], v[234:237], v[160:163], v[34:37]
	v_mfma_f32_16x16x32_bf16 v[22:25], v[204:207], v[188:191], v[22:25]
	v_mfma_f32_16x16x32_bf16 v[18:21], v[234:237], v[188:191], v[18:21]
	v_mfma_f32_16x16x32_bf16 v[6:9], v[204:207], v[196:199], v[6:9]
	v_mfma_f32_16x16x32_bf16 v[2:5], v[234:237], v[196:199], v[2:5]
	v_mfma_f32_16x16x32_bf16 v[54:57], v[208:211], v[156:159], v[54:57]
	v_mfma_f32_16x16x32_bf16 v[50:53], v[238:241], v[156:159], v[50:53]
	v_mfma_f32_16x16x32_bf16 v[38:41], v[208:211], v[184:187], v[38:41]
	v_mfma_f32_16x16x32_bf16 v[34:37], v[238:241], v[184:187], v[34:37]
	v_mfma_f32_16x16x32_bf16 v[22:25], v[208:211], v[192:195], v[22:25]
	v_mfma_f32_16x16x32_bf16 v[18:21], v[238:241], v[192:195], v[18:21]
	v_mfma_f32_16x16x32_bf16 v[6:9], v[208:211], v[200:203], v[6:9]
	v_mfma_f32_16x16x32_bf16 v[2:5], v[238:241], v[200:203], v[2:5]
	s_barrier
	s_add_i32 s4, 0, 0x18000
	ds_read_b128 v[136:139], v246
	ds_read_b128 v[140:143], v246 offset:1024
	ds_read_b128 v[144:147], v246 offset:2048
	ds_read_b128 v[148:151], v246 offset:3072
	s_mov_b32 m0, s64
	ds_read_b128 v[152:155], v233 offset:32768
	ds_read_b128 v[156:159], v233 offset:33792
	ds_read_b128 v[160:163], v233 offset:34816
	ds_read_b128 v[184:187], v233 offset:35840
	ds_read_b128 v[188:191], v233 offset:36864
	ds_read_b128 v[192:195], v233 offset:37888
	ds_read_b128 v[196:199], v233 offset:38912
	ds_read_b128 v[200:203], v233 offset:39936
	global_load_lds_dwordx4 v174, s[98:99]
	s_mov_b32 m0, s65
	s_nop 0
	global_load_lds_dwordx4 v176, s[98:99]
	s_waitcnt lgkmcnt(8)
	s_barrier
; #define PG8_STAGE(bufoff, gbase, voff) do { _Pragma("unroll") for (int _i = 0; _i < 2; ++_i) \
;         __builtin_amdgcn_global_load_lds((const unsigned*)((const char*)(gbase) + (voff)[_i]), (LAS unsigned*)(lds + (bufoff) + ldsw + _i * 8192), 16, 0, 0); } while (0)
; #define PG8_LDA(dst, b, h) do { _Pragma("unroll") for (int m = 0; m < 4; ++m) _Pragma("unroll") for (int k = 0; k < 2; ++k) dst[m][k] = *(const LAS bf16x8*)(lds + PG8_SA(b, h) + aoff + m * 2048 + k * 1024); } while (0)
; #define PG8_LDB(dst, b, h) do { _Pragma("unroll") for (int n = 0; n < 2; ++n) _Pragma("unroll") for (int k = 0; k < 2; ++k) dst[n][k] = *(const LAS bf16x8*)(lds + PG8_SB(b, h) + boff + n * 2048 + k * 1024); } while (0)
; #define PG8_MMA(ai, bj, At, Bt) do { __builtin_amdgcn_s_setprio(1); _Pragma("unroll") for (int m = 0; m < 4; ++m) _Pragma("unroll") for (int n = 0; n < 2; ++n) _Pragma("unroll") for (int k = 0; k < 2; ++k) \
;         acc[ai][bj][m][n] = __builtin_amdgcn_mfma_f32_16x16x32_bf16(Bt[n][k], At[m][k], acc[ai][bj][m][n], 0, 0, 0); __builtin_amdgcn_s_setprio(0); } while (0)
; #define PG8_WAIT_V(n) asm volatile("s_waitcnt vmcnt(" #n ")" ::: "memory")
; #define PG8_WAIT_L(n) asm volatile("s_waitcnt lgkmcnt(" #n ")" ::: "memory")
; #define PG8_BAR __builtin_amdgcn_s_barrier()
; #define PG8_SCHED __builtin_amdgcn_sched_barrier(0)
; __device__ __forceinline__ void gemm_epilogue(const GemmD& g, const f32x4 (&acc)[2][2][4][2], const Unit& u, int wr, int wc, int fr, int fq) {
;     const int row0 = u.pm * BM + wr * 64 + fr;
;     const int mode = g.mode;
;     if (u.part >= 0) {
; __device__ __forceinline__ void gemm_phase(LAS unsigned char* lds, const GemmD& g) {
;     ...
;             PG8_WAIT_L(8); PG8_BAR; PG8_WAIT_L(0); PG8_MMA(0, 0, At, B0); PG8_BAR; PG8_SCHED;
;             PG8_LDB(B1, 1, 1); PG8_STAGE(PG8_SB(1, 0), b3, voffB);
;             PG8_BAR; PG8_WAIT_L(0); PG8_MMA(0, 1, At, B1); PG8_BAR;
;             PG8_LDA(At, 1, 1); PG8_STAGE(PG8_SA(1, 0), a3, voffA);
;             PG8_BAR; PG8_WAIT_L(0); PG8_MMA(1, 0, At, B0); PG8_BAR; PG8_SCHED;
;             PG8_STAGE(PG8_SB(1, 1), b3 + hstep, voffB);
;             PG8_WAIT_V(6); PG8_BAR; PG8_MMA(1, 1, At, B1); PG8_BAR;
;         }
	s_waitcnt lgkmcnt(0)
	v_mfma_f32_16x16x32_bf16 v[126:129], v[136:139], v[152:155], v[126:129]
	v_mfma_f32_16x16x32_bf16 v[122:125], v[144:147], v[152:155], v[122:125]
	v_mfma_f32_16x16x32_bf16 v[110:113], v[136:139], v[160:163], v[110:113]
	v_mfma_f32_16x16x32_bf16 v[106:109], v[144:147], v[160:163], v[106:109]
	v_mfma_f32_16x16x32_bf16 v[94:97], v[136:139], v[188:191], v[94:97]
	v_mfma_f32_16x16x32_bf16 v[90:93], v[144:147], v[188:191], v[90:93]
	v_mfma_f32_16x16x32_bf16 v[78:81], v[136:139], v[196:199], v[78:81]
	v_mfma_f32_16x16x32_bf16 v[74:77], v[144:147], v[196:199], v[74:77]
	v_mfma_f32_16x16x32_bf16 v[126:129], v[140:143], v[156:159], v[126:129]
	v_mfma_f32_16x16x32_bf16 v[122:125], v[148:151], v[156:159], v[122:125]
	v_mfma_f32_16x16x32_bf16 v[110:113], v[140:143], v[184:187], v[110:113]
	v_mfma_f32_16x16x32_bf16 v[106:109], v[148:151], v[184:187], v[106:109]
	v_mfma_f32_16x16x32_bf16 v[94:97], v[140:143], v[192:195], v[94:97]
	v_mfma_f32_16x16x32_bf16 v[90:93], v[148:151], v[192:195], v[90:93]
	v_mfma_f32_16x16x32_bf16 v[78:81], v[140:143], v[200:203], v[78:81]
	v_mfma_f32_16x16x32_bf16 v[74:77], v[148:151], v[200:203], v[74:77]
	s_barrier
	s_add_i32 s6, 0, 0x1c000
	s_add_i32 s4, s4, s87
	ds_read_b128 v[204:207], v247
	ds_read_b128 v[208:211], v247 offset:1024
	ds_read_b128 v[234:237], v247 offset:2048
	ds_read_b128 v[238:241], v247 offset:3072
	s_add_u32 s100, s100, 0x80
	s_addc_u32 s101, s101, 0
	s_mov_b32 m0, s4
	s_nop 0
	global_load_lds_dwordx4 v172, s[100:101]
	s_add_i32 m0, s4, 0x2000
	s_nop 0
	global_load_lds_dwordx4 v168, s[100:101]
	s_barrier
	s_waitcnt lgkmcnt(0)
	v_mfma_f32_16x16x32_bf16 v[118:121], v[204:207], v[152:155], v[118:121]
	v_mfma_f32_16x16x32_bf16 v[114:117], v[234:237], v[152:155], v[114:117]
	v_mfma_f32_16x16x32_bf16 v[102:105], v[204:207], v[160:163], v[102:105]
	v_mfma_f32_16x16x32_bf16 v[98:101], v[234:237], v[160:163], v[98:101]
	v_mfma_f32_16x16x32_bf16 v[86:89], v[204:207], v[188:191], v[86:89]
	v_mfma_f32_16x16x32_bf16 v[82:85], v[234:237], v[188:191], v[82:85]
	v_mfma_f32_16x16x32_bf16 v[70:73], v[204:207], v[196:199], v[70:73]
	v_mfma_f32_16x16x32_bf16 v[66:69], v[234:237], v[196:199], v[66:69]
	v_mfma_f32_16x16x32_bf16 v[118:121], v[208:211], v[156:159], v[118:121]
	v_mfma_f32_16x16x32_bf16 v[114:117], v[238:241], v[156:159], v[114:117]
	v_mfma_f32_16x16x32_bf16 v[102:105], v[208:211], v[184:187], v[102:105]
	v_mfma_f32_16x16x32_bf16 v[98:101], v[238:241], v[184:187], v[98:101]
	v_mfma_f32_16x16x32_bf16 v[86:89], v[208:211], v[192:195], v[86:89]
	v_mfma_f32_16x16x32_bf16 v[82:85], v[238:241], v[192:195], v[82:85]
	v_mfma_f32_16x16x32_bf16 v[70:73], v[208:211], v[200:203], v[70:73]
	v_mfma_f32_16x16x32_bf16 v[66:69], v[238:241], v[200:203], v[66:69]
	s_barrier
	s_mov_b32 m0, s28
	s_add_u32 s98, s98, 0x80
	s_addc_u32 s99, s99, 0
	ds_read_b128 v[152:155], v233 offset:49152
	ds_read_b128 v[156:159], v233 offset:50176
	ds_read_b128 v[160:163], v233 offset:51200
	ds_read_b128 v[184:187], v233 offset:52224
	ds_read_b128 v[188:191], v233 offset:53248
	ds_read_b128 v[192:195], v233 offset:54272
	ds_read_b128 v[196:199], v233 offset:55296
	ds_read_b128 v[200:203], v233 offset:56320
	global_load_lds_dwordx4 v170, s[98:99]
	s_mov_b32 m0, s29
	s_nop 0
	global_load_lds_dwordx4 v166, s[98:99]
	s_barrier
	s_waitcnt lgkmcnt(0)
	v_mfma_f32_16x16x32_bf16 v[62:65], v[136:139], v[152:155], v[62:65]
	v_mfma_f32_16x16x32_bf16 v[58:61], v[144:147], v[152:155], v[58:61]
	v_mfma_f32_16x16x32_bf16 v[46:49], v[136:139], v[160:163], v[46:49]
	v_mfma_f32_16x16x32_bf16 v[42:45], v[144:147], v[160:163], v[42:45]
	v_mfma_f32_16x16x32_bf16 v[30:33], v[136:139], v[188:191], v[30:33]
	v_mfma_f32_16x16x32_bf16 v[26:29], v[144:147], v[188:191], v[26:29]
	v_mfma_f32_16x16x32_bf16 v[14:17], v[136:139], v[196:199], v[14:17]
	v_mfma_f32_16x16x32_bf16 v[10:13], v[144:147], v[196:199], v[10:13]
	v_mfma_f32_16x16x32_bf16 v[62:65], v[140:143], v[156:159], v[62:65]
	v_mfma_f32_16x16x32_bf16 v[58:61], v[148:151], v[156:159], v[58:61]
	v_mfma_f32_16x16x32_bf16 v[46:49], v[140:143], v[184:187], v[46:49]
	v_mfma_f32_16x16x32_bf16 v[42:45], v[148:151], v[184:187], v[42:45]
	v_mfma_f32_16x16x32_bf16 v[30:33], v[140:143], v[192:195], v[30:33]
	v_mfma_f32_16x16x32_bf16 v[26:29], v[148:151], v[192:195], v[26:29]
	v_mfma_f32_16x16x32_bf16 v[14:17], v[140:143], v[200:203], v[14:17]
	v_mfma_f32_16x16x32_bf16 v[10:13], v[148:151], v[200:203], v[10:13]
	s_barrier
	s_add_i32 s4, s6, s87
	s_mov_b32 m0, s4
	s_nop 0
	global_load_lds_dwordx4 v242, s[100:101]
	s_add_i32 m0, s4, 0x2000
	s_nop 0
	global_load_lds_dwordx4 v243, s[100:101]
	s_add_u32 s100, s100, 0x80
	s_addc_u32 s101, s101, 0
	s_sub_u32 s5, s5, 1
	s_waitcnt vmcnt(6)
	s_barrier
	v_mfma_f32_16x16x32_bf16 v[54:57], v[204:207], v[152:155], v[54:57]
	v_mfma_f32_16x16x32_bf16 v[50:53], v[234:237], v[152:155], v[50:53]
	v_mfma_f32_16x16x32_bf16 v[38:41], v[204:207], v[160:163], v[38:41]
	v_mfma_f32_16x16x32_bf16 v[34:37], v[234:237], v[160:163], v[34:37]
	v_mfma_f32_16x16x32_bf16 v[22:25], v[204:207], v[188:191], v[22:25]
	v_mfma_f32_16x16x32_bf16 v[18:21], v[234:237], v[188:191], v[18:21]
	v_mfma_f32_16x16x32_bf16 v[6:9], v[204:207], v[196:199], v[6:9]
	v_mfma_f32_16x16x32_bf16 v[2:5], v[234:237], v[196:199], v[2:5]
	v_mfma_f32_16x16x32_bf16 v[54:57], v[208:211], v[156:159], v[54:57]
	v_mfma_f32_16x16x32_bf16 v[50:53], v[238:241], v[156:159], v[50:53]
	v_mfma_f32_16x16x32_bf16 v[38:41], v[208:211], v[184:187], v[38:41]
	v_mfma_f32_16x16x32_bf16 v[34:37], v[238:241], v[184:187], v[34:37]
	v_mfma_f32_16x16x32_bf16 v[22:25], v[208:211], v[192:195], v[22:25]
	v_mfma_f32_16x16x32_bf16 v[18:21], v[238:241], v[192:195], v[18:21]
	v_mfma_f32_16x16x32_bf16 v[6:9], v[208:211], v[200:203], v[6:9]
	v_mfma_f32_16x16x32_bf16 v[2:5], v[238:241], v[200:203], v[2:5]
	s_barrier
	s_cbranch_scc0 .LBB0_145
	v_lshl_add_u32 v184, s56, 8, v228
	s_cmp_lt_i32 s66, 0
	s_mov_b64 s[4:5], -1
	s_cbranch_scc0 .LBB0_704
